# P2 gate tiles: non-temporal stores for the gate matrix (written in P2, re-read only in P5 after attention)
# speedup vs baseline: 1.0080x; 1.0080x over previous
.LBB0_221:
	s_and_b64 vcc, exec, s[6:7]
	s_cbranch_vccz .LBB0_335
	s_lshl_b32 s4, s70, 8
	s_add_i32 s30, s4, 0xfffff700
	v_readlane_b32 s52, v254, 28
	v_or_b32_e32 v164, s30, v191
	v_readlane_b32 s60, v254, 36
	v_readlane_b32 s61, v254, 37
	v_ashrrev_i32_e32 v183, 31, v182
	v_lshlrev_b64 v[144:145], 12, v[182:183]
	v_lshl_add_u64 v[128:129], v[164:165], 2, s[60:61]
	global_load_dwordx4 v[140:143], v[128:129], off
	global_load_dwordx4 v[136:139], v[128:129], off offset:16
	global_load_dwordx4 v[132:135], v[128:129], off offset:128
	s_nop 0
	global_load_dwordx4 v[128:131], v[128:129], off offset:144
	v_lshl_add_u64 v[144:145], s[26:27], 0, v[144:145]
	s_mov_b32 s93, s31
	v_lshl_add_u64 v[144:145], s[30:31], 1, v[144:145]
	v_lshlrev_b32_e32 v164, 1, v168
	s_mov_b32 s4, 0x8000
	v_readlane_b32 s53, v254, 29
	v_readlane_b32 s54, v254, 30
	v_readlane_b32 s55, v254, 31
	v_readlane_b32 s56, v254, 32
	v_readlane_b32 s57, v254, 33
	v_readlane_b32 s58, v254, 34
	v_readlane_b32 s59, v254, 35
	v_readlane_b32 s62, v254, 38
	v_readlane_b32 s63, v254, 39
	v_readlane_b32 s64, v254, 40
	v_readlane_b32 s65, v254, 41
	v_readlane_b32 s66, v254, 42
	v_readlane_b32 s67, v254, 43
	s_waitcnt vmcnt(0)
	v_add_f32_e32 v124, v124, v140
	v_add_f32_e32 v125, v125, v141
	v_add_f32_e32 v126, v126, v142
	v_add_f32_e32 v127, v127, v143
	v_add_f32_e32 v120, v120, v136
	v_add_f32_e32 v121, v121, v137
	v_add_f32_e32 v122, v122, v138
	v_add_f32_e32 v123, v123, v139
	v_add_f32_e32 v114, v114, v130
	v_add_f32_e32 v115, v115, v131
	v_add_f32_e32 v116, v116, v132
	v_add_f32_e32 v117, v117, v133
	v_add_f32_e32 v118, v118, v134
	v_add_f32_e32 v119, v119, v135
	v_add_f32_e32 v112, v112, v128
	v_add_f32_e32 v113, v113, v129
	v_mul_f32_e32 v124, 0xbfb8aa3b, v124
	v_mul_f32_e32 v125, 0xbfb8aa3b, v125
	v_mul_f32_e32 v126, 0xbfb8aa3b, v126
	v_mul_f32_e32 v127, 0xbfb8aa3b, v127
	v_mul_f32_e32 v120, 0xbfb8aa3b, v120
	v_mul_f32_e32 v121, 0xbfb8aa3b, v121
	v_mul_f32_e32 v122, 0xbfb8aa3b, v122
	v_mul_f32_e32 v123, 0xbfb8aa3b, v123
	v_mul_f32_e32 v114, 0xbfb8aa3b, v114
	v_mul_f32_e32 v115, 0xbfb8aa3b, v115
	v_mul_f32_e32 v116, 0xbfb8aa3b, v116
	v_mul_f32_e32 v117, 0xbfb8aa3b, v117
	v_mul_f32_e32 v118, 0xbfb8aa3b, v118
	v_mul_f32_e32 v119, 0xbfb8aa3b, v119
	v_mul_f32_e32 v112, 0xbfb8aa3b, v112
	v_mul_f32_e32 v113, 0xbfb8aa3b, v113
	v_exp_f32_e32 v124, v124
	v_exp_f32_e32 v125, v125
	v_exp_f32_e32 v126, v126
	v_exp_f32_e32 v127, v127
	v_exp_f32_e32 v120, v120
	v_exp_f32_e32 v121, v121
	v_exp_f32_e32 v122, v122
	v_exp_f32_e32 v123, v123
	v_exp_f32_e32 v114, v114
	v_exp_f32_e32 v115, v115
	v_exp_f32_e32 v116, v116
	v_exp_f32_e32 v117, v117
	v_exp_f32_e32 v118, v118
	v_exp_f32_e32 v119, v119
	v_exp_f32_e32 v112, v112
	v_exp_f32_e32 v113, v113
	v_add_f32_e32 v124, 1.0, v124
	v_add_f32_e32 v125, 1.0, v125
	v_add_f32_e32 v126, 1.0, v126
	v_add_f32_e32 v127, 1.0, v127
	v_add_f32_e32 v120, 1.0, v120
	v_add_f32_e32 v121, 1.0, v121
	v_add_f32_e32 v122, 1.0, v122
	v_add_f32_e32 v123, 1.0, v123
	v_add_f32_e32 v114, 1.0, v114
	v_add_f32_e32 v115, 1.0, v115
	v_add_f32_e32 v116, 1.0, v116
	v_add_f32_e32 v117, 1.0, v117
	v_add_f32_e32 v118, 1.0, v118
	v_add_f32_e32 v119, 1.0, v119
	v_add_f32_e32 v112, 1.0, v112
	v_add_f32_e32 v113, 1.0, v113
	v_rcp_f32_e32 v124, v124
	v_rcp_f32_e32 v125, v125
	v_rcp_f32_e32 v126, v126
	v_rcp_f32_e32 v127, v127
	v_rcp_f32_e32 v120, v120
	v_rcp_f32_e32 v121, v121
	v_rcp_f32_e32 v122, v122
	v_rcp_f32_e32 v123, v123
	v_rcp_f32_e32 v114, v114
	v_rcp_f32_e32 v115, v115
	v_rcp_f32_e32 v146, v116
	v_rcp_f32_e32 v147, v117
	v_rcp_f32_e32 v148, v118
	v_rcp_f32_e32 v149, v119
	v_rcp_f32_e32 v112, v112
	v_rcp_f32_e32 v113, v113
	v_cvt_pk_bf16_f32 v116, v124, v125
	v_cvt_pk_bf16_f32 v117, v126, v127
	v_cvt_pk_bf16_f32 v118, v120, v121
	v_cvt_pk_bf16_f32 v119, v122, v123
	v_cvt_pk_bf16_f32 v123, v114, v115
	v_add_u32_e32 v114, v192, v169
	v_cvt_pk_bf16_f32 v120, v146, v147
	v_cvt_pk_bf16_f32 v121, v148, v149
	v_cvt_pk_bf16_f32 v122, v112, v113
	ds_write_b128 v114, v[116:119]
	ds_write_b128 v114, v[120:123] offset:64
	v_add_u32_e32 v115, v193, v190
	ds_read_b128 v[116:119], v115
	ds_read_b128 v[120:123], v115 offset:1152
	v_add_f32_e32 v104, v104, v136
	v_mul_f32_e32 v104, 0xbfb8aa3b, v104
	v_add_f32_e32 v105, v105, v137
	v_exp_f32_e32 v104, v104
	v_mul_f32_e32 v105, 0xbfb8aa3b, v105
	v_lshl_add_u64 v[112:113], v[144:145], 0, s[92:93]
	v_exp_f32_e32 v105, v105
	v_lshl_add_u64 v[112:113], v[112:113], 0, v[164:165]
	v_add_f32_e32 v108, v108, v140
	v_add_f32_e32 v109, v109, v141
	s_waitcnt lgkmcnt(1)
	global_store_dwordx4 v[112:113], v[116:119], off nt
	v_mul_f32_e32 v108, 0xbfb8aa3b, v108
	v_mul_f32_e32 v109, 0xbfb8aa3b, v109
	v_add_co_u32_e32 v116, vcc, s4, v112
	v_exp_f32_e32 v108, v108
	s_nop 0
	v_addc_co_u32_e32 v117, vcc, 0, v113, vcc
	v_exp_f32_e32 v109, v109
	v_add_f32_e32 v104, 1.0, v104
	s_waitcnt lgkmcnt(0)
	global_store_dwordx4 v[116:117], v[120:123], off nt
	v_rcp_f32_e32 v116, v104
	v_add_f32_e32 v104, 1.0, v105
	v_add_f32_e32 v105, v106, v138
	v_mul_f32_e32 v105, 0xbfb8aa3b, v105
	v_add_f32_e32 v106, v107, v139
	v_add_f32_e32 v96, v96, v128
	v_exp_f32_e32 v105, v105
	v_mul_f32_e32 v106, 0xbfb8aa3b, v106
	v_mul_f32_e32 v96, 0xbfb8aa3b, v96
	v_add_f32_e32 v97, v97, v129
	v_add_f32_e32 v108, 1.0, v108
	v_add_f32_e32 v109, 1.0, v109
	v_exp_f32_e32 v106, v106
	v_exp_f32_e32 v96, v96
	v_mul_f32_e32 v97, 0xbfb8aa3b, v97
	v_rcp_f32_e32 v108, v108
	v_rcp_f32_e32 v109, v109
	v_exp_f32_e32 v97, v97
	v_add_f32_e32 v110, v110, v142
	v_add_f32_e32 v111, v111, v143
	v_mul_f32_e32 v110, 0xbfb8aa3b, v110
	v_mul_f32_e32 v111, 0xbfb8aa3b, v111
	v_rcp_f32_e32 v107, v104
	v_add_f32_e32 v104, 1.0, v105
	v_exp_f32_e32 v110, v110
	v_exp_f32_e32 v111, v111
	v_rcp_f32_e32 v117, v104
	v_add_f32_e32 v104, 1.0, v106
	v_add_f32_e32 v96, 1.0, v96
	v_rcp_f32_e32 v118, v104
	v_cvt_pk_bf16_f32 v104, v108, v109
	v_rcp_f32_e32 v108, v96
	v_add_f32_e32 v96, 1.0, v97
	v_add_f32_e32 v97, v98, v130
	v_add_f32_e32 v100, v100, v132
	v_add_f32_e32 v101, v101, v133
	v_add_f32_e32 v102, v102, v134
	v_add_f32_e32 v103, v103, v135
	v_mul_f32_e32 v97, 0xbfb8aa3b, v97
	v_add_f32_e32 v98, v99, v131
	v_mul_f32_e32 v100, 0xbfb8aa3b, v100
	v_mul_f32_e32 v101, 0xbfb8aa3b, v101
	v_mul_f32_e32 v102, 0xbfb8aa3b, v102
	v_mul_f32_e32 v103, 0xbfb8aa3b, v103
	v_exp_f32_e32 v97, v97
	v_mul_f32_e32 v98, 0xbfb8aa3b, v98
	v_add_f32_e32 v110, 1.0, v110
	v_add_f32_e32 v111, 1.0, v111
	v_exp_f32_e32 v100, v100
	v_exp_f32_e32 v101, v101
	v_exp_f32_e32 v102, v102
	v_exp_f32_e32 v103, v103
	v_exp_f32_e32 v98, v98
	v_rcp_f32_e32 v110, v110
	v_rcp_f32_e32 v111, v111
	v_rcp_f32_e32 v99, v96
	v_add_f32_e32 v96, 1.0, v97
	v_add_f32_e32 v100, 1.0, v100
	v_add_f32_e32 v101, 1.0, v101
	v_add_f32_e32 v102, 1.0, v102
	v_add_f32_e32 v103, 1.0, v103
	v_rcp_f32_e32 v109, v96
	v_add_f32_e32 v96, 1.0, v98
	v_cvt_pk_bf16_f32 v105, v110, v111
	v_rcp_f32_e32 v100, v100
	v_rcp_f32_e32 v101, v101
	v_rcp_f32_e32 v102, v102
	v_rcp_f32_e32 v103, v103
	v_rcp_f32_e32 v110, v96
	v_cvt_pk_bf16_f32 v106, v116, v107
	v_cvt_pk_bf16_f32 v107, v117, v118
	v_cvt_pk_bf16_f32 v96, v100, v101
	v_cvt_pk_bf16_f32 v97, v102, v103
	v_cvt_pk_bf16_f32 v98, v108, v99
	v_cvt_pk_bf16_f32 v99, v109, v110
	ds_write_b128 v114, v[104:107]
	ds_write_b128 v114, v[96:99] offset:64
	v_add_f32_e32 v88, v88, v136
	ds_read_b128 v[96:99], v115
	ds_read_b128 v[100:103], v115 offset:1152
	v_mul_f32_e32 v88, 0xbfb8aa3b, v88
	v_add_f32_e32 v89, v89, v137
	s_mov_b32 s4, 0x10000
	v_exp_f32_e32 v88, v88
	v_mul_f32_e32 v89, 0xbfb8aa3b, v89
	v_add_co_u32_e32 v104, vcc, s4, v112
	v_exp_f32_e32 v89, v89
	s_nop 0
	v_addc_co_u32_e32 v105, vcc, 0, v113, vcc
	s_mov_b32 s4, 0x18000
	v_add_f32_e32 v92, v92, v140
	v_add_f32_e32 v93, v93, v141
	s_waitcnt lgkmcnt(1)
	global_store_dwordx4 v[104:105], v[96:99], off nt
	v_mul_f32_e32 v92, 0xbfb8aa3b, v92
	v_mul_f32_e32 v93, 0xbfb8aa3b, v93
	v_add_co_u32_e32 v96, vcc, s4, v112
	v_exp_f32_e32 v92, v92
	s_nop 0
	v_addc_co_u32_e32 v97, vcc, 0, v113, vcc
	v_exp_f32_e32 v93, v93
	v_add_f32_e32 v88, 1.0, v88
	s_waitcnt lgkmcnt(0)
	global_store_dwordx4 v[96:97], v[100:103], off nt
	v_rcp_f32_e32 v96, v88
	v_add_f32_e32 v88, 1.0, v89
	v_add_f32_e32 v89, v90, v138
	v_mul_f32_e32 v89, 0xbfb8aa3b, v89
	v_add_f32_e32 v90, v91, v139
	v_add_f32_e32 v80, v80, v128
	v_exp_f32_e32 v89, v89
	v_mul_f32_e32 v90, 0xbfb8aa3b, v90
	v_mul_f32_e32 v80, 0xbfb8aa3b, v80
	v_add_f32_e32 v81, v81, v129
	v_add_f32_e32 v92, 1.0, v92
	v_add_f32_e32 v93, 1.0, v93
	v_exp_f32_e32 v90, v90
	v_exp_f32_e32 v80, v80
	v_mul_f32_e32 v81, 0xbfb8aa3b, v81
	v_rcp_f32_e32 v92, v92
	v_rcp_f32_e32 v93, v93
	v_exp_f32_e32 v81, v81
	v_add_f32_e32 v94, v94, v142
	v_add_f32_e32 v95, v95, v143
	v_mul_f32_e32 v94, 0xbfb8aa3b, v94
	v_mul_f32_e32 v95, 0xbfb8aa3b, v95
	v_rcp_f32_e32 v91, v88
	v_add_f32_e32 v88, 1.0, v89
	v_exp_f32_e32 v94, v94
	v_exp_f32_e32 v95, v95
	v_rcp_f32_e32 v97, v88
	v_add_f32_e32 v88, 1.0, v90
	v_add_f32_e32 v80, 1.0, v80
	v_rcp_f32_e32 v98, v88
	v_cvt_pk_bf16_f32 v88, v92, v93
	v_rcp_f32_e32 v92, v80
	v_add_f32_e32 v80, 1.0, v81
	v_add_f32_e32 v81, v82, v130
	v_add_f32_e32 v84, v84, v132
	v_add_f32_e32 v85, v85, v133
	v_add_f32_e32 v86, v86, v134
	v_add_f32_e32 v87, v87, v135
	v_mul_f32_e32 v81, 0xbfb8aa3b, v81
	v_add_f32_e32 v82, v83, v131
	v_mul_f32_e32 v84, 0xbfb8aa3b, v84
	v_mul_f32_e32 v85, 0xbfb8aa3b, v85
	v_mul_f32_e32 v86, 0xbfb8aa3b, v86
	v_mul_f32_e32 v87, 0xbfb8aa3b, v87
	v_exp_f32_e32 v81, v81
	v_mul_f32_e32 v82, 0xbfb8aa3b, v82
	v_add_f32_e32 v94, 1.0, v94
	v_add_f32_e32 v95, 1.0, v95
	v_exp_f32_e32 v84, v84
	v_exp_f32_e32 v85, v85
	v_exp_f32_e32 v86, v86
	v_exp_f32_e32 v87, v87
	v_exp_f32_e32 v82, v82
	v_rcp_f32_e32 v94, v94
	v_rcp_f32_e32 v95, v95
	v_rcp_f32_e32 v83, v80
	v_add_f32_e32 v80, 1.0, v81
	v_add_f32_e32 v84, 1.0, v84
	v_add_f32_e32 v85, 1.0, v85
	v_add_f32_e32 v86, 1.0, v86
	v_add_f32_e32 v87, 1.0, v87
	v_rcp_f32_e32 v93, v80
	v_add_f32_e32 v80, 1.0, v82
	v_cvt_pk_bf16_f32 v89, v94, v95
	v_rcp_f32_e32 v84, v84
	v_rcp_f32_e32 v85, v85
	v_rcp_f32_e32 v86, v86
	v_rcp_f32_e32 v87, v87
	v_rcp_f32_e32 v94, v80
	v_cvt_pk_bf16_f32 v90, v96, v91
	v_cvt_pk_bf16_f32 v91, v97, v98
	v_cvt_pk_bf16_f32 v80, v84, v85
	v_cvt_pk_bf16_f32 v81, v86, v87
	v_cvt_pk_bf16_f32 v82, v92, v83
	v_cvt_pk_bf16_f32 v83, v93, v94
	ds_write_b128 v114, v[88:91]
	ds_write_b128 v114, v[80:83] offset:64
	v_add_f32_e32 v72, v72, v136
	ds_read_b128 v[80:83], v115
	ds_read_b128 v[84:87], v115 offset:1152
	v_mul_f32_e32 v72, 0xbfb8aa3b, v72
	v_add_f32_e32 v73, v73, v137
	s_mov_b32 s4, 0x20000
	v_exp_f32_e32 v72, v72
	v_mul_f32_e32 v73, 0xbfb8aa3b, v73
	v_add_co_u32_e32 v88, vcc, s4, v112
	v_exp_f32_e32 v73, v73
	s_nop 0
	v_addc_co_u32_e32 v89, vcc, 0, v113, vcc
	s_mov_b32 s4, 0x28000
	v_add_f32_e32 v76, v76, v140
	v_add_f32_e32 v77, v77, v141
	s_waitcnt lgkmcnt(1)
	global_store_dwordx4 v[88:89], v[80:83], off nt
	v_mul_f32_e32 v76, 0xbfb8aa3b, v76
	v_mul_f32_e32 v77, 0xbfb8aa3b, v77
	v_add_co_u32_e32 v80, vcc, s4, v112
	v_exp_f32_e32 v76, v76
	s_nop 0
	v_addc_co_u32_e32 v81, vcc, 0, v113, vcc
	v_exp_f32_e32 v77, v77
	v_add_f32_e32 v72, 1.0, v72
	s_waitcnt lgkmcnt(0)
	global_store_dwordx4 v[80:81], v[84:87], off nt
	v_rcp_f32_e32 v80, v72
	v_add_f32_e32 v72, 1.0, v73
	v_add_f32_e32 v73, v74, v138
	v_mul_f32_e32 v73, 0xbfb8aa3b, v73
	v_add_f32_e32 v74, v75, v139
	v_add_f32_e32 v64, v64, v128
	v_exp_f32_e32 v73, v73
	v_mul_f32_e32 v74, 0xbfb8aa3b, v74
	v_mul_f32_e32 v64, 0xbfb8aa3b, v64
	v_add_f32_e32 v65, v65, v129
	v_add_f32_e32 v76, 1.0, v76
	v_add_f32_e32 v77, 1.0, v77
	v_exp_f32_e32 v74, v74
	v_exp_f32_e32 v64, v64
	v_mul_f32_e32 v65, 0xbfb8aa3b, v65
	v_rcp_f32_e32 v76, v76
	v_rcp_f32_e32 v77, v77
	v_exp_f32_e32 v65, v65
	v_add_f32_e32 v78, v78, v142
	v_add_f32_e32 v79, v79, v143
	v_mul_f32_e32 v78, 0xbfb8aa3b, v78
	v_mul_f32_e32 v79, 0xbfb8aa3b, v79
	v_rcp_f32_e32 v75, v72
	v_add_f32_e32 v72, 1.0, v73
	v_exp_f32_e32 v78, v78
	v_exp_f32_e32 v79, v79
	v_rcp_f32_e32 v81, v72
	v_add_f32_e32 v72, 1.0, v74
	v_add_f32_e32 v64, 1.0, v64
	v_rcp_f32_e32 v82, v72
	v_cvt_pk_bf16_f32 v72, v76, v77
	v_rcp_f32_e32 v76, v64
	v_add_f32_e32 v64, 1.0, v65
	v_add_f32_e32 v65, v66, v130
	v_add_f32_e32 v68, v68, v132
	v_add_f32_e32 v69, v69, v133
	v_add_f32_e32 v70, v70, v134
	v_add_f32_e32 v71, v71, v135
	v_mul_f32_e32 v65, 0xbfb8aa3b, v65
	v_add_f32_e32 v66, v67, v131
	v_mul_f32_e32 v68, 0xbfb8aa3b, v68
	v_mul_f32_e32 v69, 0xbfb8aa3b, v69
	v_mul_f32_e32 v70, 0xbfb8aa3b, v70
	v_mul_f32_e32 v71, 0xbfb8aa3b, v71
	v_exp_f32_e32 v65, v65
	v_mul_f32_e32 v66, 0xbfb8aa3b, v66
	v_add_f32_e32 v78, 1.0, v78
	v_add_f32_e32 v79, 1.0, v79
	v_exp_f32_e32 v68, v68
	v_exp_f32_e32 v69, v69
	v_exp_f32_e32 v70, v70
	v_exp_f32_e32 v71, v71
	v_exp_f32_e32 v66, v66
	v_rcp_f32_e32 v78, v78
	v_rcp_f32_e32 v79, v79
	v_rcp_f32_e32 v67, v64
	v_add_f32_e32 v64, 1.0, v65
	v_add_f32_e32 v68, 1.0, v68
	v_add_f32_e32 v69, 1.0, v69
	v_add_f32_e32 v70, 1.0, v70
	v_add_f32_e32 v71, 1.0, v71
	v_rcp_f32_e32 v77, v64
	v_add_f32_e32 v64, 1.0, v66
	v_cvt_pk_bf16_f32 v73, v78, v79
	v_rcp_f32_e32 v68, v68
	v_rcp_f32_e32 v69, v69
	v_rcp_f32_e32 v70, v70
	v_rcp_f32_e32 v71, v71
	v_rcp_f32_e32 v78, v64
	v_cvt_pk_bf16_f32 v74, v80, v75
	v_cvt_pk_bf16_f32 v75, v81, v82
	v_cvt_pk_bf16_f32 v64, v68, v69
	v_cvt_pk_bf16_f32 v65, v70, v71
	v_cvt_pk_bf16_f32 v66, v76, v67
	v_cvt_pk_bf16_f32 v67, v77, v78
	ds_write_b128 v114, v[72:75]
	ds_write_b128 v114, v[64:67] offset:64
	v_add_f32_e32 v56, v56, v136
	ds_read_b128 v[64:67], v115
	ds_read_b128 v[68:71], v115 offset:1152
	v_mul_f32_e32 v56, 0xbfb8aa3b, v56
	v_add_f32_e32 v57, v57, v137
	s_mov_b32 s4, 0x30000
	v_exp_f32_e32 v56, v56
	v_mul_f32_e32 v57, 0xbfb8aa3b, v57
	v_add_co_u32_e32 v72, vcc, s4, v112
	v_exp_f32_e32 v57, v57
	s_nop 0
	v_addc_co_u32_e32 v73, vcc, 0, v113, vcc
	s_mov_b32 s4, 0x38000
	v_add_f32_e32 v60, v60, v140
	v_add_f32_e32 v61, v61, v141
	s_waitcnt lgkmcnt(1)
	global_store_dwordx4 v[72:73], v[64:67], off nt
	v_mul_f32_e32 v60, 0xbfb8aa3b, v60
	v_mul_f32_e32 v61, 0xbfb8aa3b, v61
	v_add_co_u32_e32 v64, vcc, s4, v112
	v_exp_f32_e32 v60, v60
	s_nop 0
	v_addc_co_u32_e32 v65, vcc, 0, v113, vcc
	v_exp_f32_e32 v61, v61
	v_add_f32_e32 v56, 1.0, v56
	s_waitcnt lgkmcnt(0)
	global_store_dwordx4 v[64:65], v[68:71], off nt
	v_rcp_f32_e32 v64, v56
	v_add_f32_e32 v56, 1.0, v57
	v_add_f32_e32 v57, v58, v138
	v_mul_f32_e32 v57, 0xbfb8aa3b, v57
	v_add_f32_e32 v58, v59, v139
	v_add_f32_e32 v48, v48, v128
	v_exp_f32_e32 v57, v57
	v_mul_f32_e32 v58, 0xbfb8aa3b, v58
	v_mul_f32_e32 v48, 0xbfb8aa3b, v48
	v_add_f32_e32 v49, v49, v129
	v_add_f32_e32 v60, 1.0, v60
	v_add_f32_e32 v61, 1.0, v61
	v_exp_f32_e32 v58, v58
	v_exp_f32_e32 v48, v48
	v_mul_f32_e32 v49, 0xbfb8aa3b, v49
	v_rcp_f32_e32 v60, v60
	v_rcp_f32_e32 v61, v61
	v_exp_f32_e32 v49, v49
	v_add_f32_e32 v62, v62, v142
	v_add_f32_e32 v63, v63, v143
	v_mul_f32_e32 v62, 0xbfb8aa3b, v62
	v_mul_f32_e32 v63, 0xbfb8aa3b, v63
	v_rcp_f32_e32 v59, v56
	v_add_f32_e32 v56, 1.0, v57
	v_exp_f32_e32 v62, v62
	v_exp_f32_e32 v63, v63
	v_rcp_f32_e32 v65, v56
	v_add_f32_e32 v56, 1.0, v58
	v_add_f32_e32 v48, 1.0, v48
	v_rcp_f32_e32 v66, v56
	v_cvt_pk_bf16_f32 v56, v60, v61
	v_rcp_f32_e32 v60, v48
	v_add_f32_e32 v48, 1.0, v49
	v_add_f32_e32 v49, v50, v130
	v_add_f32_e32 v52, v52, v132
	v_add_f32_e32 v53, v53, v133
	v_add_f32_e32 v54, v54, v134
	v_add_f32_e32 v55, v55, v135
	v_mul_f32_e32 v49, 0xbfb8aa3b, v49
	v_add_f32_e32 v50, v51, v131
	v_mul_f32_e32 v52, 0xbfb8aa3b, v52
	v_mul_f32_e32 v53, 0xbfb8aa3b, v53
	v_mul_f32_e32 v54, 0xbfb8aa3b, v54
	v_mul_f32_e32 v55, 0xbfb8aa3b, v55
	v_exp_f32_e32 v49, v49
	v_mul_f32_e32 v50, 0xbfb8aa3b, v50
	v_add_f32_e32 v62, 1.0, v62
	v_add_f32_e32 v63, 1.0, v63
	v_exp_f32_e32 v52, v52
	v_exp_f32_e32 v53, v53
	v_exp_f32_e32 v54, v54
	v_exp_f32_e32 v55, v55
	v_exp_f32_e32 v50, v50
	v_rcp_f32_e32 v62, v62
	v_rcp_f32_e32 v63, v63
	v_rcp_f32_e32 v51, v48
	v_add_f32_e32 v48, 1.0, v49
	v_add_f32_e32 v52, 1.0, v52
	v_add_f32_e32 v53, 1.0, v53
	v_add_f32_e32 v54, 1.0, v54
	v_add_f32_e32 v55, 1.0, v55
	v_rcp_f32_e32 v61, v48
	v_add_f32_e32 v48, 1.0, v50
	v_cvt_pk_bf16_f32 v57, v62, v63
	v_rcp_f32_e32 v52, v52
	v_rcp_f32_e32 v53, v53
	v_rcp_f32_e32 v54, v54
	v_rcp_f32_e32 v55, v55
	v_rcp_f32_e32 v62, v48
	v_cvt_pk_bf16_f32 v58, v64, v59
	v_cvt_pk_bf16_f32 v59, v65, v66
	v_cvt_pk_bf16_f32 v48, v52, v53
	v_cvt_pk_bf16_f32 v49, v54, v55
	v_cvt_pk_bf16_f32 v50, v60, v51
	v_cvt_pk_bf16_f32 v51, v61, v62
	ds_write_b128 v114, v[56:59]
	ds_write_b128 v114, v[48:51] offset:64
	v_add_f32_e32 v40, v40, v136
	ds_read_b128 v[48:51], v115
	ds_read_b128 v[52:55], v115 offset:1152
	v_mul_f32_e32 v40, 0xbfb8aa3b, v40
	v_add_f32_e32 v41, v41, v137
	s_mov_b32 s4, 0x80000
	v_exp_f32_e32 v40, v40
	v_mul_f32_e32 v41, 0xbfb8aa3b, v41
	v_add_co_u32_e32 v56, vcc, s4, v112
	v_exp_f32_e32 v41, v41
	s_nop 0
	v_addc_co_u32_e32 v57, vcc, 0, v113, vcc
	s_mov_b32 s4, 0x88000
	v_add_f32_e32 v44, v44, v140
	v_add_f32_e32 v45, v45, v141
	s_waitcnt lgkmcnt(1)
	global_store_dwordx4 v[56:57], v[48:51], off nt
	v_mul_f32_e32 v44, 0xbfb8aa3b, v44
	v_mul_f32_e32 v45, 0xbfb8aa3b, v45
	v_add_co_u32_e32 v48, vcc, s4, v112
	v_exp_f32_e32 v44, v44
	s_nop 0
	v_addc_co_u32_e32 v49, vcc, 0, v113, vcc
	v_exp_f32_e32 v45, v45
	v_add_f32_e32 v40, 1.0, v40
	s_waitcnt lgkmcnt(0)
	global_store_dwordx4 v[48:49], v[52:55], off nt
	v_rcp_f32_e32 v48, v40
	v_add_f32_e32 v40, 1.0, v41
	v_add_f32_e32 v41, v42, v138
	v_mul_f32_e32 v41, 0xbfb8aa3b, v41
	v_add_f32_e32 v42, v43, v139
	v_add_f32_e32 v32, v32, v128
	v_exp_f32_e32 v41, v41
	v_mul_f32_e32 v42, 0xbfb8aa3b, v42
	v_mul_f32_e32 v32, 0xbfb8aa3b, v32
	v_add_f32_e32 v33, v33, v129
	v_add_f32_e32 v44, 1.0, v44
	v_add_f32_e32 v45, 1.0, v45
	v_exp_f32_e32 v42, v42
	v_exp_f32_e32 v32, v32
	v_mul_f32_e32 v33, 0xbfb8aa3b, v33
	v_rcp_f32_e32 v44, v44
	v_rcp_f32_e32 v45, v45
	v_exp_f32_e32 v33, v33
	v_add_f32_e32 v46, v46, v142
	v_add_f32_e32 v47, v47, v143
	v_mul_f32_e32 v46, 0xbfb8aa3b, v46
	v_mul_f32_e32 v47, 0xbfb8aa3b, v47
	v_rcp_f32_e32 v43, v40
	v_add_f32_e32 v40, 1.0, v41
	v_exp_f32_e32 v46, v46
	v_exp_f32_e32 v47, v47
	v_rcp_f32_e32 v49, v40
	v_add_f32_e32 v40, 1.0, v42
	v_add_f32_e32 v32, 1.0, v32
	v_rcp_f32_e32 v50, v40
	v_cvt_pk_bf16_f32 v40, v44, v45
	v_rcp_f32_e32 v44, v32
	v_add_f32_e32 v32, 1.0, v33
	v_add_f32_e32 v33, v34, v130
	v_add_f32_e32 v36, v36, v132
	v_add_f32_e32 v37, v37, v133
	v_add_f32_e32 v38, v38, v134
	v_add_f32_e32 v39, v39, v135
	v_mul_f32_e32 v33, 0xbfb8aa3b, v33
	v_add_f32_e32 v34, v35, v131
	v_mul_f32_e32 v36, 0xbfb8aa3b, v36
	v_mul_f32_e32 v37, 0xbfb8aa3b, v37
	v_mul_f32_e32 v38, 0xbfb8aa3b, v38
	v_mul_f32_e32 v39, 0xbfb8aa3b, v39
	v_exp_f32_e32 v33, v33
	v_mul_f32_e32 v34, 0xbfb8aa3b, v34
	v_add_f32_e32 v46, 1.0, v46
	v_add_f32_e32 v47, 1.0, v47
	v_exp_f32_e32 v36, v36
	v_exp_f32_e32 v37, v37
	v_exp_f32_e32 v38, v38
	v_exp_f32_e32 v39, v39
	v_exp_f32_e32 v34, v34
	v_rcp_f32_e32 v46, v46
	v_rcp_f32_e32 v47, v47
	v_rcp_f32_e32 v35, v32
	v_add_f32_e32 v32, 1.0, v33
	v_add_f32_e32 v36, 1.0, v36
	v_add_f32_e32 v37, 1.0, v37
	v_add_f32_e32 v38, 1.0, v38
	v_add_f32_e32 v39, 1.0, v39
	v_rcp_f32_e32 v45, v32
	v_add_f32_e32 v32, 1.0, v34
	v_cvt_pk_bf16_f32 v41, v46, v47
	v_rcp_f32_e32 v36, v36
	v_rcp_f32_e32 v37, v37
	v_rcp_f32_e32 v38, v38
	v_rcp_f32_e32 v39, v39
	v_rcp_f32_e32 v46, v32
	v_cvt_pk_bf16_f32 v42, v48, v43
	v_cvt_pk_bf16_f32 v43, v49, v50
	v_cvt_pk_bf16_f32 v32, v36, v37
	v_cvt_pk_bf16_f32 v33, v38, v39
	v_cvt_pk_bf16_f32 v34, v44, v35
	v_cvt_pk_bf16_f32 v35, v45, v46
	ds_write_b128 v114, v[40:43]
	ds_write_b128 v114, v[32:35] offset:64
	v_add_f32_e32 v24, v24, v136
	ds_read_b128 v[32:35], v115
	ds_read_b128 v[36:39], v115 offset:1152
	v_mul_f32_e32 v24, 0xbfb8aa3b, v24
	v_add_f32_e32 v25, v25, v137
	s_mov_b32 s4, 0x90000
	v_exp_f32_e32 v24, v24
	v_mul_f32_e32 v25, 0xbfb8aa3b, v25
	v_add_co_u32_e32 v40, vcc, s4, v112
	v_exp_f32_e32 v25, v25
	s_nop 0
	v_addc_co_u32_e32 v41, vcc, 0, v113, vcc
	s_mov_b32 s4, 0x98000
	v_add_f32_e32 v28, v28, v140
	v_add_f32_e32 v29, v29, v141
	s_waitcnt lgkmcnt(1)
	global_store_dwordx4 v[40:41], v[32:35], off nt
	v_mul_f32_e32 v28, 0xbfb8aa3b, v28
	v_mul_f32_e32 v29, 0xbfb8aa3b, v29
	v_add_co_u32_e32 v32, vcc, s4, v112
	v_exp_f32_e32 v28, v28
	s_nop 0
	v_addc_co_u32_e32 v33, vcc, 0, v113, vcc
	v_exp_f32_e32 v29, v29
	v_add_f32_e32 v24, 1.0, v24
	s_waitcnt lgkmcnt(0)
	global_store_dwordx4 v[32:33], v[36:39], off nt
	v_rcp_f32_e32 v32, v24
	v_add_f32_e32 v24, 1.0, v25
	v_add_f32_e32 v25, v26, v138
	v_mul_f32_e32 v25, 0xbfb8aa3b, v25
	v_add_f32_e32 v26, v27, v139
	v_add_f32_e32 v16, v16, v128
	v_exp_f32_e32 v25, v25
	v_mul_f32_e32 v26, 0xbfb8aa3b, v26
	v_mul_f32_e32 v16, 0xbfb8aa3b, v16
	v_add_f32_e32 v17, v17, v129
	v_add_f32_e32 v28, 1.0, v28
	v_add_f32_e32 v29, 1.0, v29
	v_exp_f32_e32 v26, v26
	v_exp_f32_e32 v16, v16
	v_mul_f32_e32 v17, 0xbfb8aa3b, v17
	v_rcp_f32_e32 v28, v28
	v_rcp_f32_e32 v29, v29
	v_exp_f32_e32 v17, v17
	v_add_f32_e32 v30, v30, v142
	v_add_f32_e32 v31, v31, v143
	v_mul_f32_e32 v30, 0xbfb8aa3b, v30
	v_mul_f32_e32 v31, 0xbfb8aa3b, v31
	v_rcp_f32_e32 v27, v24
	v_add_f32_e32 v24, 1.0, v25
	v_exp_f32_e32 v30, v30
	v_exp_f32_e32 v31, v31
	v_rcp_f32_e32 v33, v24
	v_add_f32_e32 v24, 1.0, v26
	v_add_f32_e32 v16, 1.0, v16
	v_rcp_f32_e32 v34, v24
	v_cvt_pk_bf16_f32 v24, v28, v29
	v_rcp_f32_e32 v28, v16
	v_add_f32_e32 v16, 1.0, v17
	v_add_f32_e32 v17, v18, v130
	v_add_f32_e32 v20, v20, v132
	v_add_f32_e32 v21, v21, v133
	v_add_f32_e32 v22, v22, v134
	v_add_f32_e32 v23, v23, v135
	v_mul_f32_e32 v17, 0xbfb8aa3b, v17
	v_add_f32_e32 v18, v19, v131
	v_mul_f32_e32 v20, 0xbfb8aa3b, v20
	v_mul_f32_e32 v21, 0xbfb8aa3b, v21
	v_mul_f32_e32 v22, 0xbfb8aa3b, v22
	v_mul_f32_e32 v23, 0xbfb8aa3b, v23
	v_exp_f32_e32 v17, v17
	v_mul_f32_e32 v18, 0xbfb8aa3b, v18
	v_add_f32_e32 v30, 1.0, v30
	v_add_f32_e32 v31, 1.0, v31
	v_exp_f32_e32 v20, v20
	v_exp_f32_e32 v21, v21
	v_exp_f32_e32 v22, v22
	v_exp_f32_e32 v23, v23
	v_exp_f32_e32 v18, v18
	v_rcp_f32_e32 v30, v30
	v_rcp_f32_e32 v31, v31
	v_rcp_f32_e32 v19, v16
	v_add_f32_e32 v16, 1.0, v17
	v_add_f32_e32 v20, 1.0, v20
	v_add_f32_e32 v21, 1.0, v21
	v_add_f32_e32 v22, 1.0, v22
	v_add_f32_e32 v23, 1.0, v23
	v_rcp_f32_e32 v29, v16
	v_add_f32_e32 v16, 1.0, v18
	v_cvt_pk_bf16_f32 v25, v30, v31
	v_rcp_f32_e32 v20, v20
	v_rcp_f32_e32 v21, v21
	v_rcp_f32_e32 v22, v22
	v_rcp_f32_e32 v23, v23
	v_rcp_f32_e32 v30, v16
	v_cvt_pk_bf16_f32 v26, v32, v27
	v_cvt_pk_bf16_f32 v27, v33, v34
	v_cvt_pk_bf16_f32 v16, v20, v21
	v_cvt_pk_bf16_f32 v17, v22, v23
	v_cvt_pk_bf16_f32 v18, v28, v19
	v_cvt_pk_bf16_f32 v19, v29, v30
	ds_write_b128 v114, v[24:27]
	ds_write_b128 v114, v[16:19] offset:64
	v_add_f32_e32 v8, v8, v136
	ds_read_b128 v[16:19], v115
	ds_read_b128 v[20:23], v115 offset:1152
	v_mul_f32_e32 v8, 0xbfb8aa3b, v8
	v_add_f32_e32 v9, v9, v137
	s_mov_b32 s4, 0xa0000
	v_exp_f32_e32 v8, v8
	v_mul_f32_e32 v9, 0xbfb8aa3b, v9
	v_add_co_u32_e32 v24, vcc, s4, v112
	v_exp_f32_e32 v9, v9
	s_nop 0
	v_addc_co_u32_e32 v25, vcc, 0, v113, vcc
	s_mov_b32 s4, 0xa8000
	v_add_f32_e32 v12, v12, v140
	v_add_f32_e32 v13, v13, v141
	s_waitcnt lgkmcnt(1)
	global_store_dwordx4 v[24:25], v[16:19], off nt
	v_mul_f32_e32 v12, 0xbfb8aa3b, v12
	v_mul_f32_e32 v13, 0xbfb8aa3b, v13
	v_add_co_u32_e32 v16, vcc, s4, v112
	v_exp_f32_e32 v12, v12
	s_nop 0
	v_addc_co_u32_e32 v17, vcc, 0, v113, vcc
	v_exp_f32_e32 v13, v13
	v_add_f32_e32 v8, 1.0, v8
	s_waitcnt lgkmcnt(0)
	global_store_dwordx4 v[16:17], v[20:23], off nt
	v_rcp_f32_e32 v16, v8
	v_add_f32_e32 v8, 1.0, v9
	v_add_f32_e32 v9, v10, v138
	v_mul_f32_e32 v9, 0xbfb8aa3b, v9
	v_add_f32_e32 v10, v11, v139
	v_add_f32_e32 v0, v0, v128
	v_exp_f32_e32 v9, v9
	v_mul_f32_e32 v10, 0xbfb8aa3b, v10
	v_mul_f32_e32 v0, 0xbfb8aa3b, v0
	v_add_f32_e32 v1, v1, v129
	v_add_f32_e32 v12, 1.0, v12
	v_add_f32_e32 v13, 1.0, v13
	v_exp_f32_e32 v10, v10
	v_exp_f32_e32 v0, v0
	v_mul_f32_e32 v1, 0xbfb8aa3b, v1
	v_rcp_f32_e32 v12, v12
	v_rcp_f32_e32 v13, v13
	v_exp_f32_e32 v1, v1
	v_add_f32_e32 v14, v14, v142
	v_add_f32_e32 v15, v15, v143
	v_mul_f32_e32 v14, 0xbfb8aa3b, v14
	v_mul_f32_e32 v15, 0xbfb8aa3b, v15
	v_rcp_f32_e32 v11, v8
	v_add_f32_e32 v8, 1.0, v9
	v_exp_f32_e32 v14, v14
	v_exp_f32_e32 v15, v15
	v_rcp_f32_e32 v17, v8
	v_add_f32_e32 v8, 1.0, v10
	v_add_f32_e32 v0, 1.0, v0
	v_rcp_f32_e32 v18, v8
	v_cvt_pk_bf16_f32 v8, v12, v13
	v_rcp_f32_e32 v12, v0
	v_add_f32_e32 v0, 1.0, v1
	v_add_f32_e32 v1, v2, v130
	v_add_f32_e32 v4, v4, v132
	v_add_f32_e32 v5, v5, v133
	v_add_f32_e32 v6, v6, v134
	v_add_f32_e32 v7, v7, v135
	v_mul_f32_e32 v1, 0xbfb8aa3b, v1
	v_add_f32_e32 v2, v3, v131
	v_mul_f32_e32 v4, 0xbfb8aa3b, v4
	v_mul_f32_e32 v5, 0xbfb8aa3b, v5
	v_mul_f32_e32 v6, 0xbfb8aa3b, v6
	v_mul_f32_e32 v7, 0xbfb8aa3b, v7
	v_exp_f32_e32 v1, v1
	v_mul_f32_e32 v2, 0xbfb8aa3b, v2
	v_add_f32_e32 v14, 1.0, v14
	v_add_f32_e32 v15, 1.0, v15
	v_exp_f32_e32 v4, v4
	v_exp_f32_e32 v5, v5
	v_exp_f32_e32 v6, v6
	v_exp_f32_e32 v7, v7
	v_exp_f32_e32 v2, v2
	v_rcp_f32_e32 v14, v14
	v_rcp_f32_e32 v15, v15
	v_rcp_f32_e32 v3, v0
	v_add_f32_e32 v0, 1.0, v1
	v_add_f32_e32 v4, 1.0, v4
	v_add_f32_e32 v5, 1.0, v5
	v_add_f32_e32 v6, 1.0, v6
	v_add_f32_e32 v7, 1.0, v7
	v_rcp_f32_e32 v13, v0
	v_add_f32_e32 v0, 1.0, v2
	v_cvt_pk_bf16_f32 v9, v14, v15
	v_rcp_f32_e32 v4, v4
	v_rcp_f32_e32 v5, v5
	v_rcp_f32_e32 v6, v6
	v_rcp_f32_e32 v7, v7
	v_rcp_f32_e32 v14, v0
	v_cvt_pk_bf16_f32 v10, v16, v11
	v_cvt_pk_bf16_f32 v11, v17, v18
	v_cvt_pk_bf16_f32 v0, v4, v5
	v_cvt_pk_bf16_f32 v1, v6, v7
	v_cvt_pk_bf16_f32 v2, v12, v3
	v_cvt_pk_bf16_f32 v3, v13, v14
	ds_write_b128 v114, v[8:11]
	ds_write_b128 v114, v[0:3] offset:64
	ds_read_b128 v[0:3], v115
	ds_read_b128 v[4:7], v115 offset:1152
	v_add_co_u32_e32 v8, vcc, 0xb0000, v112
	s_nop 1
	v_addc_co_u32_e32 v9, vcc, 0, v113, vcc
	s_waitcnt lgkmcnt(1)
	global_store_dwordx4 v[8:9], v[0:3], off nt
	s_nop 1
	v_add_co_u32_e32 v0, vcc, 0xb8000, v112
	s_nop 1
	v_addc_co_u32_e32 v1, vcc, 0, v113, vcc
	s_waitcnt lgkmcnt(0)
	global_store_dwordx4 v[0:1], v[4:7], off nt
	s_andn2_b64 vcc, exec, s[12:13]
	s_mov_b64 s[4:5], -1
	s_cbranch_vccnz .LBB0_204
	s_branch .LBB0_336
